# Fourier roles renumbered two per XCD, each on the XCD of the block whose o columns it writes; Fourier epilogue o stores plain L2 write-back
# baseline (speedup 1.0000x reference)
.Lvbx_odd:
	s_bfe_u32 s6, s2, 0x30003
	s_bfe_u32 s7, s2, 0x20001
	s_lshl_b32 s7, s7, 3
	s_or_b32 s6, s6, s7
	s_bfe_u32 s7, s2, 0x10006
	s_lshl_b32 s7, s7, 5
	s_or_b32 s6, s6, s7
	s_or_b32 s2, s6, 64
